# in-proj epilogue: default cache policy for SWA column tiles 24..43, nt for the rest
# baseline (speedup 1.0000x reference)
; #define PG8_STAGE(bufoff, gbase, voff) do { _Pragma("unroll") for (int _i = 0; _i < 2; ++_i) \
;         __builtin_amdgcn_global_load_lds((const unsigned*)((const char*)(gbase) + (voff)[_i]), (LAS unsigned*)(lds + (bufoff) + ldsw + _i * 8192), 16, 0, 0); } while (0)
; #define PG8_LDA(dst, b, h) do { _Pragma("unroll") for (int m = 0; m < 4; ++m) _Pragma("unroll") for (int k = 0; k < 2; ++k) dst[m][k] = *(const LAS h8*)(lds + PG8_SA(b, h) + aoff + m * 2048 + k * 1024); } while (0)
; #define PG8_LDB(dst, b, h) do { _Pragma("unroll") for (int n = 0; n < 2; ++n) _Pragma("unroll") for (int k = 0; k < 2; ++k) dst[n][k] = *(const LAS h8*)(lds + PG8_SB(b, h) + boff + n * 2048 + k * 1024); } while (0)
; #define PG8_WAIT_L(n) asm volatile("s_waitcnt lgkmcnt(" #n ")" ::: "memory")
; #define PG8_BAR __builtin_amdgcn_s_barrier()
; #define PG8_SCHED __builtin_amdgcn_sched_barrier(0)
; template <class Epi>
; __device__ __forceinline__ void gemm_phase(LAS unsigned char* lds, const Gemm g, const StaticOrder& S, const Epi& E, const int tid) {
;     ...
;             PG8_LDB(B0, 0, 0); PG8_SCHED; PG8_LDA(At, 0, 0); PG8_STAGE(PG8_SA(1, 1), a1 + hstep, voffA);
;             PG8_WAIT_L(8); PG8_BAR; PG8_WAIT_L(0); PG8_MMA(0, 0, At, B0); PG8_BAR; PG8_SCHED;
;             PG8_LDB(B1, 0, 1); PG8_STAGE(PG8_SB(0, 0), b2, voffB);
;             PG8_BAR; PG8_WAIT_L(0); PG8_MMA(0, 1, At, B1); PG8_BAR;
;             PG8_LDA(At, 0, 1); PG8_STAGE(PG8_SA(0, 0), a2, voffA);
;             PG8_BAR; PG8_WAIT_L(0); PG8_MMA(1, 0, At, B0); PG8_BAR; PG8_SCHED;
.LBB0_332:
	s_add_u32 s18, s14, 0xfff80080
	s_addc_u32 s19, s15, -1
	s_add_i32 s55, 0, 0x10000
	v_add_u32_e32 v157, s55, v140
	ds_read_b128 v[144:147], v157
	ds_read_b128 v[162:165], v157 offset:1024
	ds_read_b128 v[166:169], v157 offset:2048
	ds_read_b128 v[170:173], v157 offset:3072
	s_cmp_eq_u32 s54, 28
	s_cselect_b32 s23, s9, s19
	s_cselect_b32 s22, s50, s18
	s_cselect_b32 s19, s1, s53
	s_cselect_b32 s18, s51, s52
	v_lshl_add_u64 v[178:179], s[14:15], 0, v[136:137]
	s_add_i32 m0, s39, 0xc000
	ds_read_b128 v[174:177], v143
	ds_read_b128 v[190:193], v143 offset:1024
	ds_read_b128 v[194:197], v143 offset:2048
	ds_read_b128 v[198:201], v143 offset:3072
	ds_read_b128 v[202:205], v143 offset:4096
	ds_read_b128 v[206:209], v143 offset:5120
	ds_read_b128 v[210:213], v143 offset:6144
	ds_read_b128 v[214:217], v143 offset:7168
	global_load_lds_dwordx4 v[178:179], off
	v_lshl_add_u64 v[178:179], s[14:15], 0, v[138:139]
	s_add_i32 m0, s39, 0xe000
	s_nop 0
	global_load_lds_dwordx4 v[178:179], off
	s_waitcnt lgkmcnt(8)
	s_barrier
	s_waitcnt lgkmcnt(0)
	s_waitcnt lgkmcnt(0)
	v_mfma_f32_16x16x32_bf16 v[124:127], v[144:147], v[174:177], v[124:127]
	v_mfma_f32_16x16x32_bf16 v[128:131], v[166:169], v[174:177], v[128:131]
	v_mfma_f32_16x16x32_bf16 v[108:111], v[144:147], v[194:197], v[108:111]
	v_mfma_f32_16x16x32_bf16 v[112:115], v[166:169], v[194:197], v[112:115]
	v_mfma_f32_16x16x32_bf16 v[92:95], v[144:147], v[202:205], v[92:95]
	v_mfma_f32_16x16x32_bf16 v[96:99], v[166:169], v[202:205], v[96:99]
	v_mfma_f32_16x16x32_bf16 v[76:79], v[144:147], v[210:213], v[76:79]
	v_mfma_f32_16x16x32_bf16 v[80:83], v[166:169], v[210:213], v[80:83]
	v_mfma_f32_16x16x32_bf16 v[124:127], v[162:165], v[190:193], v[124:127]
	v_mfma_f32_16x16x32_bf16 v[128:131], v[170:173], v[190:193], v[128:131]
	v_mfma_f32_16x16x32_bf16 v[108:111], v[162:165], v[198:201], v[108:111]
	v_mfma_f32_16x16x32_bf16 v[112:115], v[170:173], v[198:201], v[112:115]
	v_mfma_f32_16x16x32_bf16 v[92:95], v[162:165], v[206:209], v[92:95]
	v_mfma_f32_16x16x32_bf16 v[96:99], v[170:173], v[206:209], v[96:99]
	v_mfma_f32_16x16x32_bf16 v[76:79], v[162:165], v[214:217], v[76:79]
	v_mfma_f32_16x16x32_bf16 v[80:83], v[170:173], v[214:217], v[80:83]
	s_barrier
	s_add_i32 s58, 0, 0x14000
	s_add_i32 s55, s55, s38
	v_add_u32_e32 v157, s58, v140
	v_lshl_add_u64 v[178:179], s[18:19], 0, v[2:3]
	s_mov_b32 m0, s55
	ds_read_b128 v[218:221], v157
	ds_read_b128 v[222:225], v157 offset:1024
	ds_read_b128 v[226:229], v157 offset:2048
	ds_read_b128 v[230:233], v157 offset:3072
	global_load_lds_dwordx4 v[178:179], off
	v_lshl_add_u64 v[234:235], s[18:19], 0, v[0:1]
	s_add_i32 m0, s55, 0x2000
	s_nop 0
	global_load_lds_dwordx4 v[234:235], off
	s_barrier
	s_waitcnt lgkmcnt(0)
	s_waitcnt lgkmcnt(0)
	v_mfma_f32_16x16x32_bf16 v[116:119], v[218:221], v[174:177], v[116:119]
	v_mfma_f32_16x16x32_bf16 v[120:123], v[226:229], v[174:177], v[120:123]
	v_mfma_f32_16x16x32_bf16 v[100:103], v[218:221], v[194:197], v[100:103]
	v_mfma_f32_16x16x32_bf16 v[104:107], v[226:229], v[194:197], v[104:107]
	v_mfma_f32_16x16x32_bf16 v[84:87], v[218:221], v[202:205], v[84:87]
	v_mfma_f32_16x16x32_bf16 v[88:91], v[226:229], v[202:205], v[88:91]
	v_mfma_f32_16x16x32_bf16 v[68:71], v[218:221], v[210:213], v[68:71]
	v_mfma_f32_16x16x32_bf16 v[72:75], v[226:229], v[210:213], v[72:75]
	v_mfma_f32_16x16x32_bf16 v[116:119], v[222:225], v[190:193], v[116:119]
	v_mfma_f32_16x16x32_bf16 v[120:123], v[230:233], v[190:193], v[120:123]
	v_mfma_f32_16x16x32_bf16 v[100:103], v[222:225], v[198:201], v[100:103]
	v_mfma_f32_16x16x32_bf16 v[104:107], v[230:233], v[198:201], v[104:107]
	v_mfma_f32_16x16x32_bf16 v[84:87], v[222:225], v[206:209], v[84:87]
	v_mfma_f32_16x16x32_bf16 v[88:91], v[230:233], v[206:209], v[88:91]
	v_mfma_f32_16x16x32_bf16 v[68:71], v[222:225], v[214:217], v[68:71]
	v_mfma_f32_16x16x32_bf16 v[72:75], v[230:233], v[214:217], v[72:75]
	s_mov_b32 m0, s39
	v_lshl_add_u64 v[236:237], s[22:23], 0, v[134:135]
	s_barrier
	ds_read_b128 v[174:177], v143 offset:16384
	ds_read_b128 v[190:193], v143 offset:17408
	ds_read_b128 v[194:197], v143 offset:18432
	ds_read_b128 v[198:201], v143 offset:19456
	ds_read_b128 v[202:205], v143 offset:20480
	ds_read_b128 v[206:209], v143 offset:21504
	ds_read_b128 v[210:213], v143 offset:22528
	ds_read_b128 v[214:217], v143 offset:23552
	global_load_lds_dwordx4 v[236:237], off
	v_lshl_add_u64 v[238:239], s[22:23], 0, v[132:133]
	s_mov_b32 m0, s40
	s_nop 0
	global_load_lds_dwordx4 v[238:239], off
	s_barrier
	s_waitcnt lgkmcnt(0)
	s_waitcnt lgkmcnt(0)
	v_mfma_f32_16x16x32_bf16 v[60:63], v[144:147], v[174:177], v[60:63]
	v_mfma_f32_16x16x32_bf16 v[64:67], v[166:169], v[174:177], v[64:67]
	v_mfma_f32_16x16x32_bf16 v[44:47], v[144:147], v[194:197], v[44:47]
	v_mfma_f32_16x16x32_bf16 v[48:51], v[166:169], v[194:197], v[48:51]
	v_mfma_f32_16x16x32_bf16 v[28:31], v[144:147], v[202:205], v[28:31]
	v_mfma_f32_16x16x32_bf16 v[32:35], v[166:169], v[202:205], v[32:35]
	v_mfma_f32_16x16x32_bf16 v[12:15], v[144:147], v[210:213], v[12:15]
	v_mfma_f32_16x16x32_bf16 v[16:19], v[166:169], v[210:213], v[16:19]
	v_mfma_f32_16x16x32_bf16 v[60:63], v[162:165], v[190:193], v[60:63]
	v_mfma_f32_16x16x32_bf16 v[64:67], v[170:173], v[190:193], v[64:67]
	v_mfma_f32_16x16x32_bf16 v[44:47], v[162:165], v[198:201], v[44:47]
	v_mfma_f32_16x16x32_bf16 v[48:51], v[170:173], v[198:201], v[48:51]
	v_mfma_f32_16x16x32_bf16 v[28:31], v[162:165], v[206:209], v[28:31]
	v_mfma_f32_16x16x32_bf16 v[32:35], v[170:173], v[206:209], v[32:35]
	v_mfma_f32_16x16x32_bf16 v[12:15], v[162:165], v[214:217], v[12:15]
	v_mfma_f32_16x16x32_bf16 v[16:19], v[170:173], v[214:217], v[16:19]
	s_barrier
; #define PG8_STAGE(bufoff, gbase, voff) do { _Pragma("unroll") for (int _i = 0; _i < 2; ++_i) \
;         __builtin_amdgcn_global_load_lds((const unsigned*)((const char*)(gbase) + (voff)[_i]), (LAS unsigned*)(lds + (bufoff) + ldsw + _i * 8192), 16, 0, 0); } while (0)
; #define PG8_LDA(dst, b, h) do { _Pragma("unroll") for (int m = 0; m < 4; ++m) _Pragma("unroll") for (int k = 0; k < 2; ++k) dst[m][k] = *(const LAS h8*)(lds + PG8_SA(b, h) + aoff + m * 2048 + k * 1024); } while (0)
; #define PG8_LDB(dst, b, h) do { _Pragma("unroll") for (int n = 0; n < 2; ++n) _Pragma("unroll") for (int k = 0; k < 2; ++k) dst[n][k] = *(const LAS h8*)(lds + PG8_SB(b, h) + boff + n * 2048 + k * 1024); } while (0)
; #define PG8_WAIT_V(n) asm volatile("s_waitcnt vmcnt(" #n ")" ::: "memory")
; #define PG8_WAIT_L(n) asm volatile("s_waitcnt lgkmcnt(" #n ")" ::: "memory")
; #define PG8_BAR __builtin_amdgcn_s_barrier()
; #define PG8_SCHED __builtin_amdgcn_sched_barrier(0)
; template <class Epi>
; __device__ __forceinline__ void gemm_phase(LAS unsigned char* lds, const Gemm g, const StaticOrder& S, const Epi& E, const int tid) {
;     ...
;             PG8_STAGE(PG8_SB(0, 1), b2 + hstepB, voffB);
;             PG8_WAIT_V(6); PG8_BAR; PG8_MMA(1, 1, At, B1); PG8_BAR;
;             PG8_LDB(B0, 1, 0); PG8_SCHED; PG8_LDA(At, 1, 0); PG8_STAGE(PG8_SA(0, 1), a2 + hstep, voffA);
;             PG8_WAIT_L(8); PG8_BAR; PG8_WAIT_L(0); PG8_MMA(0, 0, At, B0); PG8_BAR; PG8_SCHED;
;             PG8_LDB(B1, 1, 1); PG8_STAGE(PG8_SB(1, 0), b3, voffB);
;             PG8_BAR; PG8_WAIT_L(0); PG8_MMA(0, 1, At, B1); PG8_BAR;
;             PG8_LDA(At, 1, 1); PG8_STAGE(PG8_SA(1, 0), a3, voffA);
	s_add_u32 s56, s18, 0x20000
	s_addc_u32 s57, s19, 0
	s_add_i32 s55, s58, s38
	v_lshl_add_u64 v[144:145], s[56:57], 0, v[2:3]
	s_mov_b32 m0, s55
	s_nop 0
	global_load_lds_dwordx4 v[144:145], off
	v_lshl_add_u64 v[144:145], s[56:57], 0, v[0:1]
	s_add_i32 m0, s55, 0x2000
	s_nop 0
	global_load_lds_dwordx4 v[144:145], off
	s_waitcnt vmcnt(6)
	s_barrier
	v_mfma_f32_16x16x32_bf16 v[52:55], v[218:221], v[174:177], v[52:55]
	v_mfma_f32_16x16x32_bf16 v[56:59], v[226:229], v[174:177], v[56:59]
	v_mfma_f32_16x16x32_bf16 v[36:39], v[218:221], v[194:197], v[36:39]
	v_mfma_f32_16x16x32_bf16 v[40:43], v[226:229], v[194:197], v[40:43]
	v_mfma_f32_16x16x32_bf16 v[20:23], v[218:221], v[202:205], v[20:23]
	v_mfma_f32_16x16x32_bf16 v[24:27], v[226:229], v[202:205], v[24:27]
	v_mfma_f32_16x16x32_bf16 v[8:11], v[218:221], v[210:213], v[8:11]
	v_mfma_f32_16x16x32_bf16 v[4:7], v[226:229], v[210:213], v[4:7]
	v_mfma_f32_16x16x32_bf16 v[52:55], v[222:225], v[190:193], v[52:55]
	v_mfma_f32_16x16x32_bf16 v[56:59], v[230:233], v[190:193], v[56:59]
	v_mfma_f32_16x16x32_bf16 v[36:39], v[222:225], v[198:201], v[36:39]
	v_mfma_f32_16x16x32_bf16 v[40:43], v[230:233], v[198:201], v[40:43]
	v_mfma_f32_16x16x32_bf16 v[20:23], v[222:225], v[206:209], v[20:23]
	v_mfma_f32_16x16x32_bf16 v[24:27], v[230:233], v[206:209], v[24:27]
	v_mfma_f32_16x16x32_bf16 v[8:11], v[222:225], v[214:217], v[8:11]
	v_mfma_f32_16x16x32_bf16 v[4:7], v[230:233], v[214:217], v[4:7]
	s_add_i32 s55, 0, 0x18000
	v_add_u32_e32 v157, s55, v140
	s_barrier
	ds_read_b128 v[144:147], v157
	ds_read_b128 v[162:165], v157 offset:1024
	ds_read_b128 v[166:169], v157 offset:2048
	ds_read_b128 v[170:173], v157 offset:3072
	s_add_u32 s22, s22, 0x80000
	s_addc_u32 s23, s23, 0
	s_mov_b32 m0, s41
	v_lshl_add_u64 v[218:219], s[22:23], 0, v[134:135]
	ds_read_b128 v[174:177], v143 offset:32768
	ds_read_b128 v[190:193], v143 offset:33792
	ds_read_b128 v[194:197], v143 offset:34816
	ds_read_b128 v[198:201], v143 offset:35840
	ds_read_b128 v[202:205], v143 offset:36864
	ds_read_b128 v[206:209], v143 offset:37888
	ds_read_b128 v[210:213], v143 offset:38912
	ds_read_b128 v[214:217], v143 offset:39936
	global_load_lds_dwordx4 v[218:219], off
	v_lshl_add_u64 v[218:219], s[22:23], 0, v[132:133]
	s_mov_b32 m0, s42
	s_nop 0
	global_load_lds_dwordx4 v[218:219], off
	s_waitcnt lgkmcnt(8)
	s_barrier
	s_waitcnt lgkmcnt(0)
	s_waitcnt lgkmcnt(0)
	v_mfma_f32_16x16x32_bf16 v[124:127], v[144:147], v[174:177], v[124:127]
	v_mfma_f32_16x16x32_bf16 v[128:131], v[166:169], v[174:177], v[128:131]
	v_mfma_f32_16x16x32_bf16 v[108:111], v[144:147], v[194:197], v[108:111]
	v_mfma_f32_16x16x32_bf16 v[112:115], v[166:169], v[194:197], v[112:115]
	v_mfma_f32_16x16x32_bf16 v[92:95], v[144:147], v[202:205], v[92:95]
	v_mfma_f32_16x16x32_bf16 v[96:99], v[166:169], v[202:205], v[96:99]
	v_mfma_f32_16x16x32_bf16 v[76:79], v[144:147], v[210:213], v[76:79]
	v_mfma_f32_16x16x32_bf16 v[80:83], v[166:169], v[210:213], v[80:83]
	v_mfma_f32_16x16x32_bf16 v[124:127], v[162:165], v[190:193], v[124:127]
	v_mfma_f32_16x16x32_bf16 v[128:131], v[170:173], v[190:193], v[128:131]
	v_mfma_f32_16x16x32_bf16 v[108:111], v[162:165], v[198:201], v[108:111]
	v_mfma_f32_16x16x32_bf16 v[112:115], v[170:173], v[198:201], v[112:115]
	v_mfma_f32_16x16x32_bf16 v[92:95], v[162:165], v[206:209], v[92:95]
	v_mfma_f32_16x16x32_bf16 v[96:99], v[170:173], v[206:209], v[96:99]
	v_mfma_f32_16x16x32_bf16 v[76:79], v[162:165], v[214:217], v[76:79]
	v_mfma_f32_16x16x32_bf16 v[80:83], v[170:173], v[214:217], v[80:83]
	s_barrier
	s_add_i32 s22, 0, 0x1c000
	s_add_i32 s23, s55, s38
	v_add_u32_e32 v157, s22, v140
	v_lshl_add_u64 v[178:179], v[178:179], 0, s[30:31]
	s_mov_b32 m0, s23
	ds_read_b128 v[218:221], v157
	ds_read_b128 v[222:225], v157 offset:1024
	ds_read_b128 v[226:229], v157 offset:2048
	ds_read_b128 v[230:233], v157 offset:3072
	global_load_lds_dwordx4 v[178:179], off
	v_lshl_add_u64 v[178:179], v[234:235], 0, s[30:31]
	s_add_i32 m0, s23, 0x2000
	s_nop 0
	global_load_lds_dwordx4 v[178:179], off
	s_barrier
	s_waitcnt lgkmcnt(0)
	s_waitcnt lgkmcnt(0)
	v_mfma_f32_16x16x32_bf16 v[116:119], v[218:221], v[174:177], v[116:119]
	v_mfma_f32_16x16x32_bf16 v[120:123], v[226:229], v[174:177], v[120:123]
	v_mfma_f32_16x16x32_bf16 v[100:103], v[218:221], v[194:197], v[100:103]
	v_mfma_f32_16x16x32_bf16 v[104:107], v[226:229], v[194:197], v[104:107]
	v_mfma_f32_16x16x32_bf16 v[84:87], v[218:221], v[202:205], v[84:87]
	v_mfma_f32_16x16x32_bf16 v[88:91], v[226:229], v[202:205], v[88:91]
	v_mfma_f32_16x16x32_bf16 v[68:71], v[218:221], v[210:213], v[68:71]
	v_mfma_f32_16x16x32_bf16 v[72:75], v[226:229], v[210:213], v[72:75]
	v_mfma_f32_16x16x32_bf16 v[116:119], v[222:225], v[190:193], v[116:119]
	v_mfma_f32_16x16x32_bf16 v[120:123], v[230:233], v[190:193], v[120:123]
	v_mfma_f32_16x16x32_bf16 v[100:103], v[222:225], v[198:201], v[100:103]
	v_mfma_f32_16x16x32_bf16 v[104:107], v[230:233], v[198:201], v[104:107]
	v_mfma_f32_16x16x32_bf16 v[84:87], v[222:225], v[206:209], v[84:87]
	v_mfma_f32_16x16x32_bf16 v[88:91], v[230:233], v[206:209], v[88:91]
	v_mfma_f32_16x16x32_bf16 v[68:71], v[222:225], v[214:217], v[68:71]
	v_mfma_f32_16x16x32_bf16 v[72:75], v[230:233], v[214:217], v[72:75]
	s_mov_b32 m0, s43
	v_lshl_add_u64 v[178:179], v[236:237], 0, s[30:31]
	s_barrier
	ds_read_b128 v[174:177], v143 offset:49152
	ds_read_b128 v[190:193], v143 offset:50176
	ds_read_b128 v[194:197], v143 offset:51200
	ds_read_b128 v[198:201], v143 offset:52224
	ds_read_b128 v[202:205], v143 offset:53248
	ds_read_b128 v[206:209], v143 offset:54272
	ds_read_b128 v[210:213], v143 offset:55296
	ds_read_b128 v[214:217], v143 offset:56320
	global_load_lds_dwordx4 v[178:179], off
	v_lshl_add_u64 v[178:179], v[238:239], 0, s[30:31]
	s_mov_b32 m0, s46
	s_nop 0
	global_load_lds_dwordx4 v[178:179], off
	s_barrier
; #define PG8_STAGE(bufoff, gbase, voff) do { _Pragma("unroll") for (int _i = 0; _i < 2; ++_i) \
;         __builtin_amdgcn_global_load_lds((const unsigned*)((const char*)(gbase) + (voff)[_i]), (LAS unsigned*)(lds + (bufoff) + ldsw + _i * 8192), 16, 0, 0); } while (0)
; #define PG8_WAIT_V(n) asm volatile("s_waitcnt vmcnt(" #n ")" ::: "memory")
; #define PG8_WAIT_L(n) asm volatile("s_waitcnt lgkmcnt(" #n ")" ::: "memory")
; #define PG8_BAR __builtin_amdgcn_s_barrier()
; #define PG8_SCHED __builtin_amdgcn_sched_barrier(0)
; template <class Epi>
; __device__ __forceinline__ void gemm_phase(LAS unsigned char* lds, const Gemm g, const StaticOrder& S, const Epi& E, const int tid) {
;     ...
;             PG8_BAR; PG8_WAIT_L(0); PG8_MMA(1, 0, At, B0); PG8_BAR; PG8_SCHED;
;             PG8_STAGE(PG8_SB(1, 1), b3 + hstepB, voffB);
;             PG8_WAIT_V(6); PG8_BAR; PG8_MMA(1, 1, At, B1); PG8_BAR;
;     __device__ __forceinline__ void operator()(f32x4 (&acc)[2][2][4][2], const pg8::Unit& u, int wr, int wc, int fr, int fq) const {
;         const bool hi = fr >= 8;
;         const int row0 = u.pm * 256 + wr * 64 + (fr & 7), col = u.pn * 256 + wc * 64 + fq * 8 + (hi ? 32 : 0);
; #pragma unroll
;         for (int ai = 0; ai < 2; ++ai)
; #pragma unroll
;             for (int m = 0; m < 4; ++m) {
;                 const h8 x0 = pack8(acc[ai][0][m][0], acc[ai][0][m][1]), x1 = pack8(acc[ai][1][m][0], acc[ai][1][m][1]);
;                 const i32x4 snd = hi ? __builtin_bit_cast(i32x4, x0) : __builtin_bit_cast(i32x4, x1);
;                 i32x4 rcv;
; #pragma unroll
;                 for (int d = 0; d < 4; ++d) rcv[d] = __builtin_amdgcn_update_dpp(0, snd[d], 0x128  , 0xF, 0xF, false);
;                 const h8 rv = __builtin_bit_cast(h8, rcv);
;                 const h8 vA = hi ? rv : x0;
;                 const h8 vB = hi ? x1 : rv;
;                 half_t* rowp = O + (size_t)(row0 + ai * 128 + m * 16) * NIN + col;
;                 __builtin_nontemporal_store(vA, (h8*)rowp); __builtin_nontemporal_store(vB, (h8*)(rowp + (size_t)8 * NIN)); }
	s_waitcnt lgkmcnt(0)
	s_waitcnt lgkmcnt(0)
	v_mfma_f32_16x16x32_bf16 v[60:63], v[144:147], v[174:177], v[60:63]
	v_mfma_f32_16x16x32_bf16 v[64:67], v[166:169], v[174:177], v[64:67]
	v_mfma_f32_16x16x32_bf16 v[44:47], v[144:147], v[194:197], v[44:47]
	v_mfma_f32_16x16x32_bf16 v[48:51], v[166:169], v[194:197], v[48:51]
	v_mfma_f32_16x16x32_bf16 v[28:31], v[144:147], v[202:205], v[28:31]
	v_mfma_f32_16x16x32_bf16 v[32:35], v[166:169], v[202:205], v[32:35]
	v_mfma_f32_16x16x32_bf16 v[12:15], v[144:147], v[210:213], v[12:15]
	v_mfma_f32_16x16x32_bf16 v[16:19], v[166:169], v[210:213], v[16:19]
	v_mfma_f32_16x16x32_bf16 v[60:63], v[162:165], v[190:193], v[60:63]
	v_mfma_f32_16x16x32_bf16 v[64:67], v[170:173], v[190:193], v[64:67]
	v_mfma_f32_16x16x32_bf16 v[44:47], v[162:165], v[198:201], v[44:47]
	v_mfma_f32_16x16x32_bf16 v[48:51], v[170:173], v[198:201], v[48:51]
	v_mfma_f32_16x16x32_bf16 v[28:31], v[162:165], v[206:209], v[28:31]
	v_mfma_f32_16x16x32_bf16 v[32:35], v[170:173], v[206:209], v[32:35]
	v_mfma_f32_16x16x32_bf16 v[12:15], v[162:165], v[214:217], v[12:15]
	v_mfma_f32_16x16x32_bf16 v[16:19], v[170:173], v[214:217], v[16:19]
	s_barrier
	s_add_u32 s18, s18, 0x20080
	s_addc_u32 s19, s19, 0
	s_add_i32 s22, s22, s38
	v_lshl_add_u64 v[144:145], s[18:19], 0, v[2:3]
	s_mov_b32 m0, s22
	s_nop 0
	global_load_lds_dwordx4 v[144:145], off
	v_lshl_add_u64 v[144:145], s[18:19], 0, v[0:1]
	s_add_i32 m0, s22, 0x2000
	s_nop 0
	global_load_lds_dwordx4 v[144:145], off
	s_waitcnt vmcnt(6)
	s_barrier
	v_mfma_f32_16x16x32_bf16 v[52:55], v[218:221], v[174:177], v[52:55]
	v_mfma_f32_16x16x32_bf16 v[56:59], v[226:229], v[174:177], v[56:59]
	v_mfma_f32_16x16x32_bf16 v[36:39], v[218:221], v[194:197], v[36:39]
	v_mfma_f32_16x16x32_bf16 v[40:43], v[226:229], v[194:197], v[40:43]
	v_mfma_f32_16x16x32_bf16 v[20:23], v[218:221], v[202:205], v[20:23]
	v_mfma_f32_16x16x32_bf16 v[24:27], v[226:229], v[202:205], v[24:27]
	v_mfma_f32_16x16x32_bf16 v[8:11], v[218:221], v[210:213], v[8:11]
	v_mfma_f32_16x16x32_bf16 v[4:7], v[226:229], v[210:213], v[4:7]
	v_mfma_f32_16x16x32_bf16 v[52:55], v[222:225], v[190:193], v[52:55]
	v_mfma_f32_16x16x32_bf16 v[56:59], v[230:233], v[190:193], v[56:59]
	v_mfma_f32_16x16x32_bf16 v[36:39], v[222:225], v[198:201], v[36:39]
	v_mfma_f32_16x16x32_bf16 v[40:43], v[230:233], v[198:201], v[40:43]
	v_mfma_f32_16x16x32_bf16 v[20:23], v[222:225], v[206:209], v[20:23]
	v_mfma_f32_16x16x32_bf16 v[24:27], v[230:233], v[206:209], v[24:27]
	v_mfma_f32_16x16x32_bf16 v[8:11], v[222:225], v[214:217], v[8:11]
	v_mfma_f32_16x16x32_bf16 v[4:7], v[230:233], v[214:217], v[4:7]
	s_add_i32 s54, s54, 2
	s_add_u32 s14, s14, 0x100
	s_addc_u32 s15, s15, 0
	s_add_u32 s52, s52, 0x100
	s_addc_u32 s53, s53, 0
	s_cmp_gt_u32 s54, 29
	s_barrier
	s_cbranch_scc0 .LBB0_332
	s_cmp_lt_u32 s48, 24
	s_cbranch_scc1 .Lepi_stream
	s_cmp_lt_u32 s48, 44
	s_cbranch_scc1 .Lepi_cached
.Lepi_stream:
	v_cvt_pk_f16_f32 v124, v124, v125
	v_cvt_pk_f16_f32 v116, v116, v117
	v_cvt_pk_f16_f32 v130, v130, v131
	v_cvt_pk_f16_f32 v131, v122, v123
	v_cvt_pk_f16_f32 v128, v128, v129
	v_cvt_pk_f16_f32 v129, v120, v121
	v_cvt_pk_f16_f32 v121, v126, v127
	v_cvt_pk_f16_f32 v118, v118, v119
	v_cndmask_b32_e64 v117, v116, v124, s[4:5]
	v_mov_b32_e32 v147, v3
	v_cndmask_b32_e64 v122, v131, v130, s[4:5]
	v_cndmask_b32_e64 v119, v118, v121, s[4:5]
	v_mov_b32_dpp v147, v117 row_ror:8 row_mask:0xf bank_mask:0xf
	v_mov_b32_e32 v117, v3
	v_mov_b32_e32 v125, v3
	v_lshl_or_b32 v144, s48, 8, v142
	v_cndmask_b32_e64 v120, v129, v128, s[4:5]
	v_mov_b32_dpp v117, v119 row_ror:8 row_mask:0xf bank_mask:0xf
	v_mov_b32_e32 v119, v3
	v_mov_b32_dpp v125, v122 row_ror:8 row_mask:0xf bank_mask:0xf
	v_lshl_add_u32 v146, s49, 8, v141
	v_ashrrev_i32_e32 v145, 31, v144
	v_mov_b32_dpp v119, v120 row_ror:8 row_mask:0xf bank_mask:0xf
	v_cndmask_b32_e64 v123, v130, v125, s[4:5]
	v_cndmask_b32_e64 v121, v121, v117, s[4:5]
	v_cndmask_b32_e64 v120, v124, v147, s[4:5]
	v_cndmask_b32_e64 v127, v125, v131, s[4:5]
	v_cndmask_b32_e64 v125, v117, v118, s[4:5]
	v_cndmask_b32_e64 v124, v147, v116, s[4:5]
	v_mov_b64_e32 v[116:117], s[36:37]
	v_cndmask_b32_e64 v122, v128, v119, s[4:5]
	v_cndmask_b32_e64 v126, v119, v129, s[4:5]
	v_mad_i64_i32 v[128:129], s[14:15], v146, s35, v[116:117]
	v_lshlrev_b64 v[118:119], 1, v[144:145]
	v_lshl_add_u64 v[128:129], v[128:129], 0, v[118:119]
	s_mov_b32 s1, 0x3c000
	global_store_dwordx4 v[128:129], v[120:123], off nt
	v_cvt_pk_f16_f32 v112, v112, v113
	v_cvt_pk_f16_f32 v104, v104, v105
	v_add_co_u32_e32 v120, vcc, s1, v128
	v_cvt_pk_f16_f32 v108, v108, v109
	s_nop 0
	v_addc_co_u32_e32 v121, vcc, 0, v129, vcc
	v_cvt_pk_f16_f32 v109, v100, v101
	global_store_dwordx4 v[120:121], v[124:127], off nt
	v_cvt_pk_f16_f32 v114, v114, v115
	v_cvt_pk_f16_f32 v106, v106, v107
	v_cndmask_b32_e64 v105, v104, v112, s[4:5]
	v_cndmask_b32_e64 v100, v109, v108, s[4:5]
	v_mov_b32_e32 v113, v3
	v_mov_b32_e32 v120, v3
	v_cndmask_b32_e64 v107, v106, v114, s[4:5]
	v_cvt_pk_f16_f32 v110, v110, v111
	v_cvt_pk_f16_f32 v111, v102, v103
	v_mov_b32_dpp v113, v100 row_ror:8 row_mask:0xf bank_mask:0xf
	v_mov_b32_dpp v120, v105 row_ror:8 row_mask:0xf bank_mask:0xf
	v_mov_b32_e32 v105, v3
	v_cndmask_b32_e64 v102, v111, v110, s[4:5]
	v_mov_b32_e32 v115, v3
	v_mov_b32_dpp v105, v107 row_ror:8 row_mask:0xf bank_mask:0xf
	v_cndmask_b32_e64 v100, v108, v113, s[4:5]
	v_or_b32_e32 v108, 16, v146
	v_mov_b32_dpp v115, v102 row_ror:8 row_mask:0xf bank_mask:0xf
	v_cndmask_b32_e64 v107, v105, v106, s[4:5]
	v_cndmask_b32_e64 v106, v120, v104, s[4:5]
	v_cndmask_b32_e64 v104, v113, v109, s[4:5]
	v_mad_i64_i32 v[108:109], s[14:15], v108, s35, v[116:117]
;     __device__ __forceinline__ void operator()(f32x4 (&acc)[2][2][4][2], const pg8::Unit& u, int wr, int wc, int fr, int fq) const {
;         const bool hi = fr >= 8;
;         const int row0 = u.pm * 256 + wr * 64 + (fr & 7), col = u.pn * 256 + wc * 64 + fq * 8 + (hi ? 32 : 0);
; #pragma unroll
;         for (int ai = 0; ai < 2; ++ai)
; #pragma unroll
;             for (int m = 0; m < 4; ++m) {
;                 const h8 x0 = pack8(acc[ai][0][m][0], acc[ai][0][m][1]), x1 = pack8(acc[ai][1][m][0], acc[ai][1][m][1]);
;                 const i32x4 snd = hi ? __builtin_bit_cast(i32x4, x0) : __builtin_bit_cast(i32x4, x1);
;                 i32x4 rcv;
; #pragma unroll
;                 for (int d = 0; d < 4; ++d) rcv[d] = __builtin_amdgcn_update_dpp(0, snd[d], 0x128  , 0xF, 0xF, false);
;                 const h8 rv = __builtin_bit_cast(h8, rcv);
;                 const h8 vA = hi ? rv : x0;
;                 const h8 vB = hi ? x1 : rv;
;                 half_t* rowp = O + (size_t)(row0 + ai * 128 + m * 16) * NIN + col;
;                 __builtin_nontemporal_store(vA, (h8*)rowp); __builtin_nontemporal_store(vB, (h8*)(rowp + (size_t)8 * NIN)); }
	v_cndmask_b32_e64 v103, v114, v105, s[4:5]
	v_cndmask_b32_e64 v102, v112, v120, s[4:5]
	v_cndmask_b32_e64 v101, v110, v115, s[4:5]
	v_lshl_add_u64 v[108:109], v[108:109], 0, v[118:119]
	global_store_dwordx4 v[108:109], v[100:103], off nt
	v_cndmask_b32_e64 v105, v115, v111, s[4:5]
	v_cvt_pk_f16_f32 v96, v96, v97
	v_add_co_u32_e32 v100, vcc, s1, v108
	v_cvt_pk_f16_f32 v88, v88, v89
	s_nop 0
	v_addc_co_u32_e32 v101, vcc, 0, v109, vcc
	v_cvt_pk_f16_f32 v92, v92, v93
	v_cvt_pk_f16_f32 v93, v84, v85
	global_store_dwordx4 v[100:101], v[104:107], off nt
	v_cvt_pk_f16_f32 v98, v98, v99
	v_cvt_pk_f16_f32 v90, v90, v91
	v_cndmask_b32_e64 v89, v88, v96, s[4:5]
	v_cndmask_b32_e64 v84, v93, v92, s[4:5]
	v_mov_b32_e32 v97, v3
	v_mov_b32_e32 v100, v3
	v_cndmask_b32_e64 v91, v90, v98, s[4:5]
	v_cvt_pk_f16_f32 v94, v94, v95
	v_cvt_pk_f16_f32 v95, v86, v87
	v_mov_b32_dpp v97, v84 row_ror:8 row_mask:0xf bank_mask:0xf
	v_mov_b32_dpp v100, v89 row_ror:8 row_mask:0xf bank_mask:0xf
	v_mov_b32_e32 v89, v3
	v_cndmask_b32_e64 v86, v95, v94, s[4:5]
	v_mov_b32_e32 v99, v3
	v_mov_b32_dpp v89, v91 row_ror:8 row_mask:0xf bank_mask:0xf
	v_cndmask_b32_e64 v84, v92, v97, s[4:5]
	v_or_b32_e32 v92, 32, v146
	v_mov_b32_dpp v99, v86 row_ror:8 row_mask:0xf bank_mask:0xf
	v_cndmask_b32_e64 v91, v89, v90, s[4:5]
	v_cndmask_b32_e64 v90, v100, v88, s[4:5]
	v_cndmask_b32_e64 v88, v97, v93, s[4:5]
	v_mad_i64_i32 v[92:93], s[14:15], v92, s35, v[116:117]
	v_cndmask_b32_e64 v87, v98, v89, s[4:5]
	v_cndmask_b32_e64 v86, v96, v100, s[4:5]
	v_cndmask_b32_e64 v85, v94, v99, s[4:5]
	v_lshl_add_u64 v[92:93], v[92:93], 0, v[118:119]
	global_store_dwordx4 v[92:93], v[84:87], off nt
	v_cndmask_b32_e64 v89, v99, v95, s[4:5]
	v_cvt_pk_f16_f32 v80, v80, v81
	v_add_co_u32_e32 v84, vcc, s1, v92
	v_cvt_pk_f16_f32 v72, v72, v73
	s_nop 0
	v_addc_co_u32_e32 v85, vcc, 0, v93, vcc
	v_cvt_pk_f16_f32 v76, v76, v77
	v_cvt_pk_f16_f32 v77, v68, v69
	global_store_dwordx4 v[84:85], v[88:91], off nt
	v_cvt_pk_f16_f32 v82, v82, v83
	v_cvt_pk_f16_f32 v74, v74, v75
	v_cndmask_b32_e64 v73, v72, v80, s[4:5]
	v_cndmask_b32_e64 v68, v77, v76, s[4:5]
	v_mov_b32_e32 v81, v3
	v_mov_b32_e32 v84, v3
	v_cndmask_b32_e64 v75, v74, v82, s[4:5]
	v_cvt_pk_f16_f32 v78, v78, v79
	v_cvt_pk_f16_f32 v79, v70, v71
	v_mov_b32_dpp v81, v68 row_ror:8 row_mask:0xf bank_mask:0xf
	v_mov_b32_dpp v84, v73 row_ror:8 row_mask:0xf bank_mask:0xf
	v_mov_b32_e32 v73, v3
	v_cndmask_b32_e64 v70, v79, v78, s[4:5]
	v_mov_b32_e32 v83, v3
	v_mov_b32_dpp v73, v75 row_ror:8 row_mask:0xf bank_mask:0xf
	v_cndmask_b32_e64 v68, v76, v81, s[4:5]
	v_or_b32_e32 v76, 48, v146
	v_mov_b32_dpp v83, v70 row_ror:8 row_mask:0xf bank_mask:0xf
	v_cndmask_b32_e64 v75, v73, v74, s[4:5]
	v_cndmask_b32_e64 v74, v84, v72, s[4:5]
	v_cndmask_b32_e64 v72, v81, v77, s[4:5]
	v_mad_i64_i32 v[76:77], s[14:15], v76, s35, v[116:117]
	v_cndmask_b32_e64 v71, v82, v73, s[4:5]
	v_cndmask_b32_e64 v70, v80, v84, s[4:5]
	v_cndmask_b32_e64 v69, v78, v83, s[4:5]
	v_lshl_add_u64 v[76:77], v[76:77], 0, v[118:119]
	global_store_dwordx4 v[76:77], v[68:71], off nt
	v_cndmask_b32_e64 v73, v83, v79, s[4:5]
	v_cvt_pk_f16_f32 v64, v64, v65
	v_add_co_u32_e32 v68, vcc, s1, v76
	v_cvt_pk_f16_f32 v56, v56, v57
	s_nop 0
	v_addc_co_u32_e32 v69, vcc, 0, v77, vcc
	global_store_dwordx4 v[68:69], v[72:75], off nt
	v_cvt_pk_f16_f32 v66, v66, v67
	v_cvt_pk_f16_f32 v58, v58, v59
	v_cndmask_b32_e64 v57, v56, v64, s[4:5]
	v_cvt_pk_f16_f32 v60, v60, v61
	v_cvt_pk_f16_f32 v61, v52, v53
	v_mov_b32_e32 v69, v3
	v_cndmask_b32_e64 v59, v58, v66, s[4:5]
	v_cvt_pk_f16_f32 v62, v62, v63
	v_cvt_pk_f16_f32 v63, v54, v55
	v_cndmask_b32_e64 v52, v61, v60, s[4:5]
	v_mov_b32_e32 v65, v3
	v_mov_b32_dpp v69, v57 row_ror:8 row_mask:0xf bank_mask:0xf
	v_mov_b32_e32 v57, v3
	v_add_u32_e32 v68, 0x80, v146
	v_cndmask_b32_e64 v54, v63, v62, s[4:5]
	v_mov_b32_dpp v65, v52 row_ror:8 row_mask:0xf bank_mask:0xf
	v_mov_b32_e32 v67, v3
	v_mov_b32_dpp v57, v59 row_ror:8 row_mask:0xf bank_mask:0xf
	v_cndmask_b32_e64 v52, v60, v65, s[4:5]
	v_mov_b32_dpp v67, v54 row_ror:8 row_mask:0xf bank_mask:0xf
	v_cndmask_b32_e64 v59, v57, v58, s[4:5]
	v_cndmask_b32_e64 v58, v69, v56, s[4:5]
	v_cndmask_b32_e64 v56, v65, v61, s[4:5]
	v_mad_i64_i32 v[60:61], s[14:15], v68, s35, v[116:117]
	v_cndmask_b32_e64 v55, v66, v57, s[4:5]
	v_cndmask_b32_e64 v54, v64, v69, s[4:5]
	v_cndmask_b32_e64 v53, v62, v67, s[4:5]
	v_lshl_add_u64 v[60:61], v[60:61], 0, v[118:119]
	global_store_dwordx4 v[60:61], v[52:55], off nt
	v_cndmask_b32_e64 v57, v67, v63, s[4:5]
	v_cvt_pk_f16_f32 v48, v48, v49
	v_add_co_u32_e32 v52, vcc, s1, v60
	v_cvt_pk_f16_f32 v40, v40, v41
	s_nop 0
	v_addc_co_u32_e32 v53, vcc, 0, v61, vcc
	v_cvt_pk_f16_f32 v44, v44, v45
	v_cvt_pk_f16_f32 v45, v36, v37
	global_store_dwordx4 v[52:53], v[56:59], off nt
	v_cvt_pk_f16_f32 v50, v50, v51
	v_cvt_pk_f16_f32 v42, v42, v43
	v_cndmask_b32_e64 v41, v40, v48, s[4:5]
	v_cndmask_b32_e64 v36, v45, v44, s[4:5]
	v_mov_b32_e32 v49, v3
	v_mov_b32_e32 v52, v3
	v_cndmask_b32_e64 v43, v42, v50, s[4:5]
	v_cvt_pk_f16_f32 v46, v46, v47
	v_cvt_pk_f16_f32 v47, v38, v39
	v_mov_b32_dpp v49, v36 row_ror:8 row_mask:0xf bank_mask:0xf
	v_mov_b32_dpp v52, v41 row_ror:8 row_mask:0xf bank_mask:0xf
	v_mov_b32_e32 v41, v3
	v_cndmask_b32_e64 v38, v47, v46, s[4:5]
	v_mov_b32_e32 v51, v3
	v_mov_b32_dpp v41, v43 row_ror:8 row_mask:0xf bank_mask:0xf
	v_cndmask_b32_e64 v36, v44, v49, s[4:5]
	v_add_u32_e32 v44, 0x90, v146
	v_mov_b32_dpp v51, v38 row_ror:8 row_mask:0xf bank_mask:0xf
	v_cndmask_b32_e64 v43, v41, v42, s[4:5]
	v_cndmask_b32_e64 v42, v52, v40, s[4:5]
	v_cndmask_b32_e64 v40, v49, v45, s[4:5]
	v_mad_i64_i32 v[44:45], s[14:15], v44, s35, v[116:117]
;     __device__ __forceinline__ void operator()(f32x4 (&acc)[2][2][4][2], const pg8::Unit& u, int wr, int wc, int fr, int fq) const {
;         const bool hi = fr >= 8;
;         const int row0 = u.pm * 256 + wr * 64 + (fr & 7), col = u.pn * 256 + wc * 64 + fq * 8 + (hi ? 32 : 0);
; #pragma unroll
;         for (int ai = 0; ai < 2; ++ai)
; #pragma unroll
;             for (int m = 0; m < 4; ++m) {
;                 const h8 x0 = pack8(acc[ai][0][m][0], acc[ai][0][m][1]), x1 = pack8(acc[ai][1][m][0], acc[ai][1][m][1]);
;                 const i32x4 snd = hi ? __builtin_bit_cast(i32x4, x0) : __builtin_bit_cast(i32x4, x1);
;                 i32x4 rcv;
; #pragma unroll
;                 for (int d = 0; d < 4; ++d) rcv[d] = __builtin_amdgcn_update_dpp(0, snd[d], 0x128  , 0xF, 0xF, false);
;                 const h8 rv = __builtin_bit_cast(h8, rcv);
;                 const h8 vA = hi ? rv : x0;
;                 const h8 vB = hi ? x1 : rv;
;                 half_t* rowp = O + (size_t)(row0 + ai * 128 + m * 16) * NIN + col;
;                 __builtin_nontemporal_store(vA, (h8*)rowp); __builtin_nontemporal_store(vB, (h8*)(rowp + (size_t)8 * NIN)); }
	v_cndmask_b32_e64 v39, v50, v41, s[4:5]
	v_cndmask_b32_e64 v38, v48, v52, s[4:5]
	v_cndmask_b32_e64 v37, v46, v51, s[4:5]
	v_lshl_add_u64 v[44:45], v[44:45], 0, v[118:119]
	global_store_dwordx4 v[44:45], v[36:39], off nt
	v_cndmask_b32_e64 v41, v51, v47, s[4:5]
	v_cvt_pk_f16_f32 v32, v32, v33
	v_add_co_u32_e32 v36, vcc, s1, v44
	v_cvt_pk_f16_f32 v24, v24, v25
	s_nop 0
	v_addc_co_u32_e32 v37, vcc, 0, v45, vcc
	v_cvt_pk_f16_f32 v28, v28, v29
	v_cvt_pk_f16_f32 v29, v20, v21
	global_store_dwordx4 v[36:37], v[40:43], off nt
	v_cvt_pk_f16_f32 v34, v34, v35
	v_cvt_pk_f16_f32 v26, v26, v27
	v_cndmask_b32_e64 v25, v24, v32, s[4:5]
	v_cndmask_b32_e64 v20, v29, v28, s[4:5]
	v_mov_b32_e32 v33, v3
	v_mov_b32_e32 v36, v3
	v_cndmask_b32_e64 v27, v26, v34, s[4:5]
	v_cvt_pk_f16_f32 v30, v30, v31
	v_cvt_pk_f16_f32 v31, v22, v23
	v_mov_b32_dpp v33, v20 row_ror:8 row_mask:0xf bank_mask:0xf
	v_mov_b32_dpp v36, v25 row_ror:8 row_mask:0xf bank_mask:0xf
	v_mov_b32_e32 v25, v3
	v_cvt_pk_f16_f32 v16, v16, v17
	v_cvt_pk_f16_f32 v17, v4, v5
	v_cvt_pk_f16_f32 v5, v14, v15
	v_cvt_pk_f16_f32 v14, v10, v11
	v_cvt_pk_f16_f32 v10, v12, v13
	v_cvt_pk_f16_f32 v8, v8, v9
	v_cndmask_b32_e64 v22, v31, v30, s[4:5]
	v_mov_b32_e32 v35, v3
	v_mov_b32_dpp v25, v27 row_ror:8 row_mask:0xf bank_mask:0xf
	v_cndmask_b32_e64 v20, v28, v33, s[4:5]
	v_add_u32_e32 v28, 0xa0, v146
	v_cndmask_b32_e64 v9, v8, v10, s[4:5]
	v_mov_b32_e32 v12, v3
	v_mov_b32_dpp v35, v22 row_ror:8 row_mask:0xf bank_mask:0xf
	v_cndmask_b32_e64 v27, v25, v26, s[4:5]
	v_cndmask_b32_e64 v26, v36, v24, s[4:5]
	v_cndmask_b32_e64 v24, v33, v29, s[4:5]
	v_mad_i64_i32 v[28:29], s[14:15], v28, s35, v[116:117]
	v_cvt_pk_f16_f32 v18, v18, v19
	v_cvt_pk_f16_f32 v19, v6, v7
	v_cndmask_b32_e64 v4, v17, v16, s[4:5]
	v_mov_b32_dpp v12, v9 row_ror:8 row_mask:0xf bank_mask:0xf
	v_mov_b32_e32 v13, v3
	v_cndmask_b32_e64 v23, v34, v25, s[4:5]
	v_cndmask_b32_e64 v22, v32, v36, s[4:5]
	v_cndmask_b32_e64 v21, v30, v35, s[4:5]
	v_lshl_add_u64 v[28:29], v[28:29], 0, v[118:119]
	v_cndmask_b32_e64 v6, v19, v18, s[4:5]
	v_cndmask_b32_e64 v7, v14, v5, s[4:5]
	v_mov_b32_e32 v9, v3
	v_mov_b32_dpp v13, v4 row_ror:8 row_mask:0xf bank_mask:0xf
	v_mov_b32_e32 v11, v3
	v_cndmask_b32_e64 v4, v10, v12, s[4:5]
	v_cndmask_b32_e64 v8, v12, v8, s[4:5]
	v_add_u32_e32 v12, 0xb0, v146
	global_store_dwordx4 v[28:29], v[20:23], off nt
	v_mov_b32_dpp v9, v7 row_ror:8 row_mask:0xf bank_mask:0xf
	v_mov_b32_dpp v11, v6 row_ror:8 row_mask:0xf bank_mask:0xf
	v_add_co_u32_e32 v20, vcc, s1, v28
	v_cndmask_b32_e64 v6, v16, v13, s[4:5]
	v_cndmask_b32_e64 v10, v13, v17, s[4:5]
	v_mad_i64_i32 v[12:13], s[14:15], v12, s35, v[116:117]
	v_addc_co_u32_e32 v21, vcc, 0, v29, vcc
	v_cndmask_b32_e64 v7, v18, v11, s[4:5]
	v_cndmask_b32_e64 v5, v5, v9, s[4:5]
	v_lshl_add_u64 v[12:13], v[12:13], 0, v[118:119]
	global_store_dwordx4 v[12:13], v[4:7], off nt
	v_cndmask_b32_e64 v25, v35, v31, s[4:5]
	v_cndmask_b32_e64 v11, v11, v19, s[4:5]
	v_add_co_u32_e32 v4, vcc, 0x3c000, v12
	v_cndmask_b32_e64 v9, v9, v14, s[4:5]
	s_nop 0
	v_addc_co_u32_e32 v5, vcc, 0, v13, vcc
	s_and_b64 vcc, exec, s[6:7]
	s_mov_b32 s48, s0
	s_mov_b32 s49, s8
	s_mov_b64 s[18:19], s[12:13]
	s_mov_b64 s[14:15], s[10:11]
	global_store_dwordx4 v[20:21], v[24:27], off nt
	global_store_dwordx4 v[4:5], v[8:11], off nt
	s_cbranch_vccz .LBB0_329
	s_branch .Lepi_join
.Lepi_cached:
	v_cvt_pk_f16_f32 v124, v124, v125
	v_cvt_pk_f16_f32 v116, v116, v117
	v_cvt_pk_f16_f32 v130, v130, v131
	v_cvt_pk_f16_f32 v131, v122, v123
	v_cvt_pk_f16_f32 v128, v128, v129
	v_cvt_pk_f16_f32 v129, v120, v121
	v_cvt_pk_f16_f32 v121, v126, v127
	v_cvt_pk_f16_f32 v118, v118, v119
	v_cndmask_b32_e64 v117, v116, v124, s[4:5]
	v_mov_b32_e32 v147, v3
	v_cndmask_b32_e64 v122, v131, v130, s[4:5]
	v_cndmask_b32_e64 v119, v118, v121, s[4:5]
	v_mov_b32_dpp v147, v117 row_ror:8 row_mask:0xf bank_mask:0xf
	v_mov_b32_e32 v117, v3
	v_mov_b32_e32 v125, v3
	v_lshl_or_b32 v144, s48, 8, v142
	v_cndmask_b32_e64 v120, v129, v128, s[4:5]
	v_mov_b32_dpp v117, v119 row_ror:8 row_mask:0xf bank_mask:0xf
	v_mov_b32_e32 v119, v3
	v_mov_b32_dpp v125, v122 row_ror:8 row_mask:0xf bank_mask:0xf
	v_lshl_add_u32 v146, s49, 8, v141
	v_ashrrev_i32_e32 v145, 31, v144
	v_mov_b32_dpp v119, v120 row_ror:8 row_mask:0xf bank_mask:0xf
	v_cndmask_b32_e64 v123, v130, v125, s[4:5]
	v_cndmask_b32_e64 v121, v121, v117, s[4:5]
	v_cndmask_b32_e64 v120, v124, v147, s[4:5]
	v_cndmask_b32_e64 v127, v125, v131, s[4:5]
	v_cndmask_b32_e64 v125, v117, v118, s[4:5]
	v_cndmask_b32_e64 v124, v147, v116, s[4:5]
	v_mov_b64_e32 v[116:117], s[36:37]
	v_cndmask_b32_e64 v122, v128, v119, s[4:5]
	v_cndmask_b32_e64 v126, v119, v129, s[4:5]
	v_mad_i64_i32 v[128:129], s[14:15], v146, s35, v[116:117]
	v_lshlrev_b64 v[118:119], 1, v[144:145]
	v_lshl_add_u64 v[128:129], v[128:129], 0, v[118:119]
	s_mov_b32 s1, 0x3c000
	global_store_dwordx4 v[128:129], v[120:123], off
	v_cvt_pk_f16_f32 v112, v112, v113
	v_cvt_pk_f16_f32 v104, v104, v105
	v_add_co_u32_e32 v120, vcc, s1, v128
	v_cvt_pk_f16_f32 v108, v108, v109
	s_nop 0
	v_addc_co_u32_e32 v121, vcc, 0, v129, vcc
	v_cvt_pk_f16_f32 v109, v100, v101
	global_store_dwordx4 v[120:121], v[124:127], off
	v_cvt_pk_f16_f32 v114, v114, v115
	v_cvt_pk_f16_f32 v106, v106, v107
	v_cndmask_b32_e64 v105, v104, v112, s[4:5]
	v_cndmask_b32_e64 v100, v109, v108, s[4:5]
	v_mov_b32_e32 v113, v3
	v_mov_b32_e32 v120, v3
	v_cndmask_b32_e64 v107, v106, v114, s[4:5]
	v_cvt_pk_f16_f32 v110, v110, v111
	v_cvt_pk_f16_f32 v111, v102, v103
	v_mov_b32_dpp v113, v100 row_ror:8 row_mask:0xf bank_mask:0xf
	v_mov_b32_dpp v120, v105 row_ror:8 row_mask:0xf bank_mask:0xf
	v_mov_b32_e32 v105, v3
;     __device__ __forceinline__ void operator()(f32x4 (&acc)[2][2][4][2], const pg8::Unit& u, int wr, int wc, int fr, int fq) const {
;         const bool hi = fr >= 8;
;         const int row0 = u.pm * 256 + wr * 64 + (fr & 7), col = u.pn * 256 + wc * 64 + fq * 8 + (hi ? 32 : 0);
; #pragma unroll
;         for (int ai = 0; ai < 2; ++ai)
; #pragma unroll
;             for (int m = 0; m < 4; ++m) {
;                 const h8 x0 = pack8(acc[ai][0][m][0], acc[ai][0][m][1]), x1 = pack8(acc[ai][1][m][0], acc[ai][1][m][1]);
;                 const i32x4 snd = hi ? __builtin_bit_cast(i32x4, x0) : __builtin_bit_cast(i32x4, x1);
;                 i32x4 rcv;
; #pragma unroll
;                 for (int d = 0; d < 4; ++d) rcv[d] = __builtin_amdgcn_update_dpp(0, snd[d], 0x128  , 0xF, 0xF, false);
;                 const h8 rv = __builtin_bit_cast(h8, rcv);
;                 const h8 vA = hi ? rv : x0;
;                 const h8 vB = hi ? x1 : rv;
;                 half_t* rowp = O + (size_t)(row0 + ai * 128 + m * 16) * NIN + col;
;                 __builtin_nontemporal_store(vA, (h8*)rowp); __builtin_nontemporal_store(vB, (h8*)(rowp + (size_t)8 * NIN)); }
	v_cndmask_b32_e64 v102, v111, v110, s[4:5]
	v_mov_b32_e32 v115, v3
	v_mov_b32_dpp v105, v107 row_ror:8 row_mask:0xf bank_mask:0xf
	v_cndmask_b32_e64 v100, v108, v113, s[4:5]
	v_or_b32_e32 v108, 16, v146
	v_mov_b32_dpp v115, v102 row_ror:8 row_mask:0xf bank_mask:0xf
	v_cndmask_b32_e64 v107, v105, v106, s[4:5]
	v_cndmask_b32_e64 v106, v120, v104, s[4:5]
	v_cndmask_b32_e64 v104, v113, v109, s[4:5]
	v_mad_i64_i32 v[108:109], s[14:15], v108, s35, v[116:117]
	v_cndmask_b32_e64 v103, v114, v105, s[4:5]
	v_cndmask_b32_e64 v102, v112, v120, s[4:5]
	v_cndmask_b32_e64 v101, v110, v115, s[4:5]
	v_lshl_add_u64 v[108:109], v[108:109], 0, v[118:119]
	global_store_dwordx4 v[108:109], v[100:103], off
	v_cndmask_b32_e64 v105, v115, v111, s[4:5]
	v_cvt_pk_f16_f32 v96, v96, v97
	v_add_co_u32_e32 v100, vcc, s1, v108
	v_cvt_pk_f16_f32 v88, v88, v89
	s_nop 0
	v_addc_co_u32_e32 v101, vcc, 0, v109, vcc
	v_cvt_pk_f16_f32 v92, v92, v93
	v_cvt_pk_f16_f32 v93, v84, v85
	global_store_dwordx4 v[100:101], v[104:107], off
	v_cvt_pk_f16_f32 v98, v98, v99
	v_cvt_pk_f16_f32 v90, v90, v91
	v_cndmask_b32_e64 v89, v88, v96, s[4:5]
	v_cndmask_b32_e64 v84, v93, v92, s[4:5]
	v_mov_b32_e32 v97, v3
	v_mov_b32_e32 v100, v3
	v_cndmask_b32_e64 v91, v90, v98, s[4:5]
	v_cvt_pk_f16_f32 v94, v94, v95
	v_cvt_pk_f16_f32 v95, v86, v87
	v_mov_b32_dpp v97, v84 row_ror:8 row_mask:0xf bank_mask:0xf
	v_mov_b32_dpp v100, v89 row_ror:8 row_mask:0xf bank_mask:0xf
	v_mov_b32_e32 v89, v3
	v_cndmask_b32_e64 v86, v95, v94, s[4:5]
	v_mov_b32_e32 v99, v3
	v_mov_b32_dpp v89, v91 row_ror:8 row_mask:0xf bank_mask:0xf
	v_cndmask_b32_e64 v84, v92, v97, s[4:5]
	v_or_b32_e32 v92, 32, v146
	v_mov_b32_dpp v99, v86 row_ror:8 row_mask:0xf bank_mask:0xf
	v_cndmask_b32_e64 v91, v89, v90, s[4:5]
	v_cndmask_b32_e64 v90, v100, v88, s[4:5]
	v_cndmask_b32_e64 v88, v97, v93, s[4:5]
	v_mad_i64_i32 v[92:93], s[14:15], v92, s35, v[116:117]
	v_cndmask_b32_e64 v87, v98, v89, s[4:5]
	v_cndmask_b32_e64 v86, v96, v100, s[4:5]
	v_cndmask_b32_e64 v85, v94, v99, s[4:5]
	v_lshl_add_u64 v[92:93], v[92:93], 0, v[118:119]
	global_store_dwordx4 v[92:93], v[84:87], off
	v_cndmask_b32_e64 v89, v99, v95, s[4:5]
	v_cvt_pk_f16_f32 v80, v80, v81
	v_add_co_u32_e32 v84, vcc, s1, v92
	v_cvt_pk_f16_f32 v72, v72, v73
	s_nop 0
	v_addc_co_u32_e32 v85, vcc, 0, v93, vcc
	v_cvt_pk_f16_f32 v76, v76, v77
	v_cvt_pk_f16_f32 v77, v68, v69
	global_store_dwordx4 v[84:85], v[88:91], off
	v_cvt_pk_f16_f32 v82, v82, v83
	v_cvt_pk_f16_f32 v74, v74, v75
	v_cndmask_b32_e64 v73, v72, v80, s[4:5]
	v_cndmask_b32_e64 v68, v77, v76, s[4:5]
	v_mov_b32_e32 v81, v3
	v_mov_b32_e32 v84, v3
	v_cndmask_b32_e64 v75, v74, v82, s[4:5]
	v_cvt_pk_f16_f32 v78, v78, v79
	v_cvt_pk_f16_f32 v79, v70, v71
	v_mov_b32_dpp v81, v68 row_ror:8 row_mask:0xf bank_mask:0xf
	v_mov_b32_dpp v84, v73 row_ror:8 row_mask:0xf bank_mask:0xf
	v_mov_b32_e32 v73, v3
	v_cndmask_b32_e64 v70, v79, v78, s[4:5]
	v_mov_b32_e32 v83, v3
	v_mov_b32_dpp v73, v75 row_ror:8 row_mask:0xf bank_mask:0xf
	v_cndmask_b32_e64 v68, v76, v81, s[4:5]
	v_or_b32_e32 v76, 48, v146
	v_mov_b32_dpp v83, v70 row_ror:8 row_mask:0xf bank_mask:0xf
	v_cndmask_b32_e64 v75, v73, v74, s[4:5]
	v_cndmask_b32_e64 v74, v84, v72, s[4:5]
	v_cndmask_b32_e64 v72, v81, v77, s[4:5]
	v_mad_i64_i32 v[76:77], s[14:15], v76, s35, v[116:117]
	v_cndmask_b32_e64 v71, v82, v73, s[4:5]
	v_cndmask_b32_e64 v70, v80, v84, s[4:5]
	v_cndmask_b32_e64 v69, v78, v83, s[4:5]
	v_lshl_add_u64 v[76:77], v[76:77], 0, v[118:119]
	global_store_dwordx4 v[76:77], v[68:71], off
	v_cndmask_b32_e64 v73, v83, v79, s[4:5]
	v_cvt_pk_f16_f32 v64, v64, v65
	v_add_co_u32_e32 v68, vcc, s1, v76
	v_cvt_pk_f16_f32 v56, v56, v57
	s_nop 0
	v_addc_co_u32_e32 v69, vcc, 0, v77, vcc
	global_store_dwordx4 v[68:69], v[72:75], off
	v_cvt_pk_f16_f32 v66, v66, v67
	v_cvt_pk_f16_f32 v58, v58, v59
	v_cndmask_b32_e64 v57, v56, v64, s[4:5]
	v_cvt_pk_f16_f32 v60, v60, v61
	v_cvt_pk_f16_f32 v61, v52, v53
	v_mov_b32_e32 v69, v3
	v_cndmask_b32_e64 v59, v58, v66, s[4:5]
	v_cvt_pk_f16_f32 v62, v62, v63
	v_cvt_pk_f16_f32 v63, v54, v55
	v_cndmask_b32_e64 v52, v61, v60, s[4:5]
	v_mov_b32_e32 v65, v3
	v_mov_b32_dpp v69, v57 row_ror:8 row_mask:0xf bank_mask:0xf
	v_mov_b32_e32 v57, v3
	v_add_u32_e32 v68, 0x80, v146
	v_cndmask_b32_e64 v54, v63, v62, s[4:5]
	v_mov_b32_dpp v65, v52 row_ror:8 row_mask:0xf bank_mask:0xf
	v_mov_b32_e32 v67, v3
	v_mov_b32_dpp v57, v59 row_ror:8 row_mask:0xf bank_mask:0xf
	v_cndmask_b32_e64 v52, v60, v65, s[4:5]
	v_mov_b32_dpp v67, v54 row_ror:8 row_mask:0xf bank_mask:0xf
	v_cndmask_b32_e64 v59, v57, v58, s[4:5]
	v_cndmask_b32_e64 v58, v69, v56, s[4:5]
	v_cndmask_b32_e64 v56, v65, v61, s[4:5]
	v_mad_i64_i32 v[60:61], s[14:15], v68, s35, v[116:117]
	v_cndmask_b32_e64 v55, v66, v57, s[4:5]
	v_cndmask_b32_e64 v54, v64, v69, s[4:5]
	v_cndmask_b32_e64 v53, v62, v67, s[4:5]
; #define PG8_WAIT_V(n) asm volatile("s_waitcnt vmcnt(" #n ")" ::: "memory")
; #define PG8_BAR __builtin_amdgcn_s_barrier()
; template <class Epi>
; __device__ __forceinline__ void gemm_phase(LAS unsigned char* lds, const Gemm g, const StaticOrder& S, const Epi& E, const int tid) {
;     ...
;     PG8_WAIT_V(0);
;     if (wr == 0) PG8_BAR;
;     PG8_BAR;
;     __device__ __forceinline__ void operator()(f32x4 (&acc)[2][2][4][2], const pg8::Unit& u, int wr, int wc, int fr, int fq) const {
;         const bool hi = fr >= 8;
;         const int row0 = u.pm * 256 + wr * 64 + (fr & 7), col = u.pn * 256 + wc * 64 + fq * 8 + (hi ? 32 : 0);
; #pragma unroll
;         for (int ai = 0; ai < 2; ++ai)
; #pragma unroll
;             for (int m = 0; m < 4; ++m) {
;                 const h8 x0 = pack8(acc[ai][0][m][0], acc[ai][0][m][1]), x1 = pack8(acc[ai][1][m][0], acc[ai][1][m][1]);
;                 const i32x4 snd = hi ? __builtin_bit_cast(i32x4, x0) : __builtin_bit_cast(i32x4, x1);
;                 i32x4 rcv;
; #pragma unroll
;                 for (int d = 0; d < 4; ++d) rcv[d] = __builtin_amdgcn_update_dpp(0, snd[d], 0x128  , 0xF, 0xF, false);
;                 const h8 rv = __builtin_bit_cast(h8, rcv);
;                 const h8 vA = hi ? rv : x0;
;                 const h8 vB = hi ? x1 : rv;
;                 half_t* rowp = O + (size_t)(row0 + ai * 128 + m * 16) * NIN + col;
;                 __builtin_nontemporal_store(vA, (h8*)rowp); __builtin_nontemporal_store(vB, (h8*)(rowp + (size_t)8 * NIN)); }
	v_lshl_add_u64 v[60:61], v[60:61], 0, v[118:119]
	global_store_dwordx4 v[60:61], v[52:55], off
	v_cndmask_b32_e64 v57, v67, v63, s[4:5]
	v_cvt_pk_f16_f32 v48, v48, v49
	v_add_co_u32_e32 v52, vcc, s1, v60
	v_cvt_pk_f16_f32 v40, v40, v41
	s_nop 0
	v_addc_co_u32_e32 v53, vcc, 0, v61, vcc
	v_cvt_pk_f16_f32 v44, v44, v45
	v_cvt_pk_f16_f32 v45, v36, v37
	global_store_dwordx4 v[52:53], v[56:59], off
	v_cvt_pk_f16_f32 v50, v50, v51
	v_cvt_pk_f16_f32 v42, v42, v43
	v_cndmask_b32_e64 v41, v40, v48, s[4:5]
	v_cndmask_b32_e64 v36, v45, v44, s[4:5]
	v_mov_b32_e32 v49, v3
	v_mov_b32_e32 v52, v3
	v_cndmask_b32_e64 v43, v42, v50, s[4:5]
	v_cvt_pk_f16_f32 v46, v46, v47
	v_cvt_pk_f16_f32 v47, v38, v39
	v_mov_b32_dpp v49, v36 row_ror:8 row_mask:0xf bank_mask:0xf
	v_mov_b32_dpp v52, v41 row_ror:8 row_mask:0xf bank_mask:0xf
	v_mov_b32_e32 v41, v3
	v_cndmask_b32_e64 v38, v47, v46, s[4:5]
	v_mov_b32_e32 v51, v3
	v_mov_b32_dpp v41, v43 row_ror:8 row_mask:0xf bank_mask:0xf
	v_cndmask_b32_e64 v36, v44, v49, s[4:5]
	v_add_u32_e32 v44, 0x90, v146
	v_mov_b32_dpp v51, v38 row_ror:8 row_mask:0xf bank_mask:0xf
	v_cndmask_b32_e64 v43, v41, v42, s[4:5]
	v_cndmask_b32_e64 v42, v52, v40, s[4:5]
	v_cndmask_b32_e64 v40, v49, v45, s[4:5]
	v_mad_i64_i32 v[44:45], s[14:15], v44, s35, v[116:117]
	v_cndmask_b32_e64 v39, v50, v41, s[4:5]
	v_cndmask_b32_e64 v38, v48, v52, s[4:5]
	v_cndmask_b32_e64 v37, v46, v51, s[4:5]
	v_lshl_add_u64 v[44:45], v[44:45], 0, v[118:119]
	global_store_dwordx4 v[44:45], v[36:39], off
	v_cndmask_b32_e64 v41, v51, v47, s[4:5]
	v_cvt_pk_f16_f32 v32, v32, v33
	v_add_co_u32_e32 v36, vcc, s1, v44
	v_cvt_pk_f16_f32 v24, v24, v25
	s_nop 0
	v_addc_co_u32_e32 v37, vcc, 0, v45, vcc
	v_cvt_pk_f16_f32 v28, v28, v29
	v_cvt_pk_f16_f32 v29, v20, v21
	global_store_dwordx4 v[36:37], v[40:43], off
	v_cvt_pk_f16_f32 v34, v34, v35
	v_cvt_pk_f16_f32 v26, v26, v27
	v_cndmask_b32_e64 v25, v24, v32, s[4:5]
	v_cndmask_b32_e64 v20, v29, v28, s[4:5]
	v_mov_b32_e32 v33, v3
	v_mov_b32_e32 v36, v3
	v_cndmask_b32_e64 v27, v26, v34, s[4:5]
	v_cvt_pk_f16_f32 v30, v30, v31
	v_cvt_pk_f16_f32 v31, v22, v23
	v_mov_b32_dpp v33, v20 row_ror:8 row_mask:0xf bank_mask:0xf
	v_mov_b32_dpp v36, v25 row_ror:8 row_mask:0xf bank_mask:0xf
	v_mov_b32_e32 v25, v3
	v_cvt_pk_f16_f32 v16, v16, v17
	v_cvt_pk_f16_f32 v17, v4, v5
	v_cvt_pk_f16_f32 v5, v14, v15
	v_cvt_pk_f16_f32 v14, v10, v11
	v_cvt_pk_f16_f32 v10, v12, v13
	v_cvt_pk_f16_f32 v8, v8, v9
	v_cndmask_b32_e64 v22, v31, v30, s[4:5]
	v_mov_b32_e32 v35, v3
	v_mov_b32_dpp v25, v27 row_ror:8 row_mask:0xf bank_mask:0xf
	v_cndmask_b32_e64 v20, v28, v33, s[4:5]
	v_add_u32_e32 v28, 0xa0, v146
	v_cndmask_b32_e64 v9, v8, v10, s[4:5]
	v_mov_b32_e32 v12, v3
	v_mov_b32_dpp v35, v22 row_ror:8 row_mask:0xf bank_mask:0xf
	v_cndmask_b32_e64 v27, v25, v26, s[4:5]
	v_cndmask_b32_e64 v26, v36, v24, s[4:5]
	v_cndmask_b32_e64 v24, v33, v29, s[4:5]
	v_mad_i64_i32 v[28:29], s[14:15], v28, s35, v[116:117]
	v_cvt_pk_f16_f32 v18, v18, v19
	v_cvt_pk_f16_f32 v19, v6, v7
	v_cndmask_b32_e64 v4, v17, v16, s[4:5]
	v_mov_b32_dpp v12, v9 row_ror:8 row_mask:0xf bank_mask:0xf
	v_mov_b32_e32 v13, v3
	v_cndmask_b32_e64 v23, v34, v25, s[4:5]
	v_cndmask_b32_e64 v22, v32, v36, s[4:5]
	v_cndmask_b32_e64 v21, v30, v35, s[4:5]
	v_lshl_add_u64 v[28:29], v[28:29], 0, v[118:119]
	v_cndmask_b32_e64 v6, v19, v18, s[4:5]
	v_cndmask_b32_e64 v7, v14, v5, s[4:5]
	v_mov_b32_e32 v9, v3
	v_mov_b32_dpp v13, v4 row_ror:8 row_mask:0xf bank_mask:0xf
	v_mov_b32_e32 v11, v3
	v_cndmask_b32_e64 v4, v10, v12, s[4:5]
	v_cndmask_b32_e64 v8, v12, v8, s[4:5]
	v_add_u32_e32 v12, 0xb0, v146
	global_store_dwordx4 v[28:29], v[20:23], off
	v_mov_b32_dpp v9, v7 row_ror:8 row_mask:0xf bank_mask:0xf
	v_mov_b32_dpp v11, v6 row_ror:8 row_mask:0xf bank_mask:0xf
	v_add_co_u32_e32 v20, vcc, s1, v28
	v_cndmask_b32_e64 v6, v16, v13, s[4:5]
	v_cndmask_b32_e64 v10, v13, v17, s[4:5]
	v_mad_i64_i32 v[12:13], s[14:15], v12, s35, v[116:117]
	v_addc_co_u32_e32 v21, vcc, 0, v29, vcc
	v_cndmask_b32_e64 v7, v18, v11, s[4:5]
	v_cndmask_b32_e64 v5, v5, v9, s[4:5]
	v_lshl_add_u64 v[12:13], v[12:13], 0, v[118:119]
	global_store_dwordx4 v[12:13], v[4:7], off
	v_cndmask_b32_e64 v25, v35, v31, s[4:5]
	v_cndmask_b32_e64 v11, v11, v19, s[4:5]
	v_add_co_u32_e32 v4, vcc, 0x3c000, v12
	v_cndmask_b32_e64 v9, v9, v14, s[4:5]
	s_nop 0
	v_addc_co_u32_e32 v5, vcc, 0, v13, vcc
	s_and_b64 vcc, exec, s[6:7]
	s_mov_b32 s48, s0
	s_mov_b32 s49, s8
	s_mov_b64 s[18:19], s[12:13]
	s_mov_b64 s[14:15], s[10:11]
	global_store_dwordx4 v[20:21], v[24:27], off
	global_store_dwordx4 v[4:5], v[8:11], off
	s_cbranch_vccz .LBB0_329
.Lepi_join:
	s_waitcnt vmcnt(0)
	v_readlane_b32 s42, v251, 7
	v_readlane_b32 s46, v251, 9
	v_readlane_b32 s48, v251, 13
	s_cmpk_gt_u32 s20, 0xff
	v_readlane_b32 s43, v251, 8
	v_readlane_b32 s47, v251, 10
	v_readlane_b32 s49, v251, 14
	s_cbranch_scc1 .LBB0_336
	s_barrier
